# baseline (speedup 1.0000x reference)
; __device__ void phase0(const Params& p) {
;     ...
;     for (int row = blockIdx.x * 8 + wid; row < MTOK; row += gridDim.x * 8) {
;       const float* xr = p.x + (size_t)row * DM;
;       float4 v[8];
;       float ss = 0.f;
; #pragma unroll
;       for (int i = 0; i < 8; ++i) {
;         v[i] = *(const float4*)(xr + (i * 64 + lane) * 4);
;         ss += v[i].x * v[i].x + v[i].y * v[i].y + v[i].z * v[i].z + v[i].w * v[i].w;
;       }
;       ss = wave_sum(ss);
;       float sc = rsqrtf(ss * (1.f / DM) + EPS);
; #pragma unroll
;       for (int i = 0; i < 8; ++i) {
;         int c = (i * 64 + lane) * 4;
;         float4 g = *(const float4*)(p.norm_mix_pre + c);
;         i32x2 o = {(int)pack2(v[i].x * sc * g.x, v[i].y * sc * g.y), (int)pack2(v[i].z * sc * g.z, v[i].w * sc * g.w)};
;         *(i32x2*)(h1 + (size_t)row * DM + c) = o;
;       }
;     }
.LBB0_10:
	s_or_b64 exec, exec, s[10:11]
	v_ashrrev_i32_e32 v1, 6, v6
	s_lshl_b32 s78, s2, 3
	v_add_u32_e32 v2, s78, v1
	s_movk_i32 s10, 0x4000
	v_cmp_gt_i32_e32 vcc, s10, v2
	v_mbcnt_lo_u32_b32 v215, -1, 0
	s_and_saveexec_b64 s[10:11], vcc
	s_cbranch_execz .LBB0_13
	v_mbcnt_hi_u32_b32 v90, -1, v215
	v_lshrrev_b32_e32 v96, 6, v214
	v_lshlrev_b32_e32 v91, 5, v90
	v_lshlrev_b32_e32 v92, 4, v90
	v_readfirstlane_b32 s16, v96
	v_add_u32_e32 v97, 0x1000, v91
	v_xor_b32_e32 v94, 16, v90
	v_xor_b32_e32 v95, 32, v90
	v_lshlrev_b32_e32 v94, 2, v94
	v_lshlrev_b32_e32 v95, 2, v95
	v_mov_b32_e32 v93, 0x358637bd
	s_nop 3
	s_add_u32 s16, s16, s78
	s_lshl_b32 s17, s33, 3
	global_load_dwordx4 v[100:103], v91, s[12:13]
	global_load_dwordx4 v[104:107], v91, s[12:13] offset:16
	global_load_dwordx4 v[108:111], v91, s[12:13] offset:2048
	global_load_dwordx4 v[112:115], v91, s[12:13] offset:2064
	global_load_dwordx4 v[116:119], v97, s[12:13]
	global_load_dwordx4 v[120:123], v97, s[12:13] offset:16
	global_load_dwordx4 v[124:127], v97, s[12:13] offset:2048
	global_load_dwordx4 v[128:131], v97, s[12:13] offset:2064
.Lnp_loop:
	s_lshl_b32 s18, s16, 13
	s_add_u32 s20, s8, s18
	s_addc_u32 s21, s9, 0
	s_lshl_b32 s18, s16, 12
	s_add_u32 s22, s14, s18
	s_addc_u32 s23, s15, 0
	global_load_dwordx4 v[16:19], v91, s[20:21]
	global_load_dwordx4 v[20:23], v91, s[20:21] offset:16
	global_load_dwordx4 v[24:27], v91, s[20:21] offset:2048
	global_load_dwordx4 v[28:31], v91, s[20:21] offset:2064
	global_load_dwordx4 v[32:35], v97, s[20:21]
	global_load_dwordx4 v[36:39], v97, s[20:21] offset:16
	global_load_dwordx4 v[40:43], v97, s[20:21] offset:2048
	global_load_dwordx4 v[44:47], v97, s[20:21] offset:2064
	s_waitcnt vmcnt(7)
	v_pk_mul_f32 v[98:99], v[16:17], v[16:17]
	v_pk_fma_f32 v[98:99], v[18:19], v[18:19], v[98:99]
	s_waitcnt vmcnt(6)
	v_pk_fma_f32 v[98:99], v[20:21], v[20:21], v[98:99]
	v_pk_fma_f32 v[98:99], v[22:23], v[22:23], v[98:99]
	s_waitcnt vmcnt(5)
	v_pk_fma_f32 v[98:99], v[24:25], v[24:25], v[98:99]
	v_pk_fma_f32 v[98:99], v[26:27], v[26:27], v[98:99]
	s_waitcnt vmcnt(4)
	v_pk_fma_f32 v[98:99], v[28:29], v[28:29], v[98:99]
	v_pk_fma_f32 v[98:99], v[30:31], v[30:31], v[98:99]
	s_waitcnt vmcnt(3)
	v_pk_fma_f32 v[98:99], v[32:33], v[32:33], v[98:99]
	v_pk_fma_f32 v[98:99], v[34:35], v[34:35], v[98:99]
	s_waitcnt vmcnt(2)
	v_pk_fma_f32 v[98:99], v[36:37], v[36:37], v[98:99]
	v_pk_fma_f32 v[98:99], v[38:39], v[38:39], v[98:99]
	s_waitcnt vmcnt(1)
	v_pk_fma_f32 v[98:99], v[40:41], v[40:41], v[98:99]
	v_pk_fma_f32 v[98:99], v[42:43], v[42:43], v[98:99]
	s_waitcnt vmcnt(0)
	v_pk_fma_f32 v[98:99], v[44:45], v[44:45], v[98:99]
	v_pk_fma_f32 v[98:99], v[46:47], v[46:47], v[98:99]
	v_add_f32_e32 v98, v98, v99
	s_nop 1
	v_add_f32_dpp v98, v98, v98 quad_perm:[1,0,3,2] row_mask:0xf bank_mask:0xf bound_ctrl:1
	s_nop 1
	v_add_f32_dpp v98, v98, v98 quad_perm:[2,3,0,1] row_mask:0xf bank_mask:0xf bound_ctrl:1
	s_nop 1
	v_add_f32_dpp v98, v98, v98 row_half_mirror row_mask:0xf bank_mask:0xf bound_ctrl:1
	s_nop 1
	v_add_f32_dpp v98, v98, v98 row_mirror row_mask:0xf bank_mask:0xf bound_ctrl:1
	s_nop 1
	ds_bpermute_b32 v96, v94, v98
	s_waitcnt lgkmcnt(0)
	v_add_f32_e32 v98, v98, v96
	s_nop 1
	ds_bpermute_b32 v96, v95, v98
	s_waitcnt lgkmcnt(0)
	v_add_f32_e32 v98, v98, v96
	v_fmamk_f32 v98, v98, 0x3a000000, v93
	v_rsq_f32_e32 v98, v98
	s_nop 1
	v_pk_mul_f32 v[48:49], v[16:17], v[98:99] op_sel_hi:[1,0]
	v_pk_mul_f32 v[50:51], v[18:19], v[98:99] op_sel_hi:[1,0]
	v_pk_mul_f32 v[52:53], v[20:21], v[98:99] op_sel_hi:[1,0]
	v_pk_mul_f32 v[54:55], v[22:23], v[98:99] op_sel_hi:[1,0]
	v_pk_mul_f32 v[56:57], v[24:25], v[98:99] op_sel_hi:[1,0]
	v_pk_mul_f32 v[58:59], v[26:27], v[98:99] op_sel_hi:[1,0]
	v_pk_mul_f32 v[60:61], v[28:29], v[98:99] op_sel_hi:[1,0]
	v_pk_mul_f32 v[62:63], v[30:31], v[98:99] op_sel_hi:[1,0]
	v_pk_mul_f32 v[64:65], v[32:33], v[98:99] op_sel_hi:[1,0]
	v_pk_mul_f32 v[66:67], v[34:35], v[98:99] op_sel_hi:[1,0]
	v_pk_mul_f32 v[68:69], v[36:37], v[98:99] op_sel_hi:[1,0]
	v_pk_mul_f32 v[70:71], v[38:39], v[98:99] op_sel_hi:[1,0]
	v_pk_mul_f32 v[72:73], v[40:41], v[98:99] op_sel_hi:[1,0]
	v_pk_mul_f32 v[74:75], v[42:43], v[98:99] op_sel_hi:[1,0]
	v_pk_mul_f32 v[76:77], v[44:45], v[98:99] op_sel_hi:[1,0]
	v_pk_mul_f32 v[78:79], v[46:47], v[98:99] op_sel_hi:[1,0]
	v_pk_mul_f32 v[48:49], v[48:49], v[100:101]
	v_pk_mul_f32 v[50:51], v[50:51], v[102:103]
	v_pk_mul_f32 v[52:53], v[52:53], v[104:105]
	v_pk_mul_f32 v[54:55], v[54:55], v[106:107]
	v_pk_mul_f32 v[56:57], v[56:57], v[108:109]
	v_pk_mul_f32 v[58:59], v[58:59], v[110:111]
	v_pk_mul_f32 v[60:61], v[60:61], v[112:113]
	v_pk_mul_f32 v[62:63], v[62:63], v[114:115]
	v_pk_mul_f32 v[64:65], v[64:65], v[116:117]
	v_pk_mul_f32 v[66:67], v[66:67], v[118:119]
	v_pk_mul_f32 v[68:69], v[68:69], v[120:121]
	v_pk_mul_f32 v[70:71], v[70:71], v[122:123]
	v_pk_mul_f32 v[72:73], v[72:73], v[124:125]
	v_pk_mul_f32 v[74:75], v[74:75], v[126:127]
	v_pk_mul_f32 v[76:77], v[76:77], v[128:129]
	v_pk_mul_f32 v[78:79], v[78:79], v[130:131]
	v_cvt_pk_bf16_f32 v0, v48, v49
	v_cvt_pk_bf16_f32 v1, v50, v51
	v_cvt_pk_bf16_f32 v2, v52, v53
	v_cvt_pk_bf16_f32 v3, v54, v55
	v_cvt_pk_bf16_f32 v4, v56, v57
	v_cvt_pk_bf16_f32 v5, v58, v59
	v_cvt_pk_bf16_f32 v6, v60, v61
	v_cvt_pk_bf16_f32 v7, v62, v63
	v_cvt_pk_bf16_f32 v8, v64, v65
	v_cvt_pk_bf16_f32 v9, v66, v67
	v_cvt_pk_bf16_f32 v10, v68, v69
	v_cvt_pk_bf16_f32 v11, v70, v71
	v_cvt_pk_bf16_f32 v12, v72, v73
	v_cvt_pk_bf16_f32 v13, v74, v75
	v_cvt_pk_bf16_f32 v14, v76, v77
	v_cvt_pk_bf16_f32 v15, v78, v79
	global_store_dwordx4 v92, v[0:3], s[22:23]
	global_store_dwordx4 v92, v[4:7], s[22:23] offset:1024
	global_store_dwordx4 v92, v[8:11], s[22:23] offset:2048
	global_store_dwordx4 v92, v[12:15], s[22:23] offset:3072
	s_add_u32 s16, s16, s17
	s_cmp_lt_u32 s16, 0x4000
	s_cbranch_scc1 .Lnp_loop

; __device__ void attn_item(const Params& p, int item, u16* O) {
;   const int tid = tid_(), wid = tid >> 6, lane = tid & 63, fr = lane & 15, g4 = lane >> 4;
;   const int qt = item & 63, hh = (item >> 6) & 15, b = item >> 10;
;   const u16* Q = (const u16*)(p.ws + OFF_Q);
;   const u16* Kg = (const u16*)(p.ws + OFF_K);
;   const u16* Vg = (const u16*)(p.ws + OFF_V);
;   u16* Ks = (u16*)g_shm;
;   u16* Vt = (u16*)(g_shm + 17408);
;   int* flags = (int*)(g_shm + 17408 + 18432);
;   const size_t tb = (size_t)b * SEQ;
;   const int q0 = qt * 128;
;   const int qrow = q0 + wid * 16 + fr;
;   bf16x8 qf[4];
; #pragma unroll
;   for (int ks = 0; ks < 4; ++ks) qf[ks] = *(const bf16x8*)(Q + (tb + qrow) * DM + hh * 128 + ks * 32 + g4 * 8);
;   f32x4 o[8];
; #pragma unroll
;   for (int i = 0; i < 8; ++i) o[i] = f32x4{0.f, 0.f, 0.f, 0.f};
;   float R = 0.f;
;   if (tid < 8) flags[tid] = 0;
;   const int kt0 = (q0 + 128) / 64 - 1;
;   i32x4 rK[2];
;   bf16x8 rV[2];
;   auto load_kv = [&](int kt) {
; #pragma unroll
;     for (int i = 0; i < 2; ++i) {
;       int idx = tid + i * NT;
;       rK[i] = *(const i32x4*)(Kg + (tb + kt * 64 + (idx >> 4)) * DM + hh * 128 + (idx & 15) * 8);
;       rV[i] = *(const bf16x8*)(Vg + (tb + kt * 64 + (idx & 63)) * DM + hh * 128 + (idx >> 6) * 8);
;     }
;   };
;   load_kv(kt0);
; template <int DUMMY>
; __device__ void phase2a(const Params& p) {
;     ...
;   if (threadIdx.x == 0) *slot = (int)atomicAdd(cnt, 1u);
;   __syncthreads();
;   int item = *slot;
;   while (item < 2048) {
;     int nxt = 0;
;     if (threadIdx.x == 0) nxt = (int)atomicAdd(cnt, 1u);
;     attn_item(p, item, DUMMY ? (u16*)(p.ws + OFF_XBC) : (u16*)(p.ws + OFF_Q));
;     if (threadIdx.x == 0) *slot = nxt;
;     __syncthreads();
;     item = *slot;
.LBB0_735:
	v_mov_b32_e32 v107, v81
	s_and_saveexec_b64 s[0:1], s[44:45]
	s_cbranch_execz .LBB0_739
	s_mov_b64 s[6:7], exec
	v_mbcnt_lo_u32_b32 v0, s6, 0
	v_mbcnt_hi_u32_b32 v0, s7, v0
	v_cmp_eq_u32_e32 vcc, 0, v0
	s_and_saveexec_b64 s[4:5], vcc
	s_cbranch_execz .LBB0_738
	s_bcnt1_i32_b64 s3, s[6:7]
	v_mov_b32_e32 v1, s3
	global_atomic_add v250, v81, v1, s[56:57] sc0
.LBB0_738:
	s_or_b64 exec, exec, s[4:5]
.LBB0_739:
	s_or_b64 exec, exec, s[0:1]
	s_ashr_i32 s0, s10, 10
	s_ashr_i32 s1, s0, 31
	v_mov_b32_e32 v30, v214
	s_lshl_b64 s[66:67], s[0:1], 13
	s_lshl_b32 s0, s10, 7
	s_and_b32 s3, s0, 0x1f80
	v_ashrrev_i32_e32 v29, 6, v30
	v_and_b32_e32 v28, 15, v30
	v_lshl_add_u32 v108, v29, 4, s3
	v_or_b32_e32 v82, v108, v28
	v_ashrrev_i32_e32 v83, 31, v82
	v_lshl_add_u64 v[0:1], s[66:67], 0, v[82:83]
	s_lshl_b32 s0, s10, 1
	v_lshlrev_b64 v[0:1], 12, v[0:1]
	s_and_b32 s0, s0, 0x780
	v_lshl_add_u64 v[0:1], s[58:59], 0, v[0:1]
	s_lshl_b32 s64, s0, 1
	v_lshl_add_u64 v[84:85], v[0:1], 0, s[64:65]
	v_and_b32_e32 v80, 48, v30
	s_waitcnt vmcnt(11)
	v_lshl_add_u64 v[16:17], v[84:85], 0, v[80:81]
	global_load_dwordx4 v[0:3], v[16:17], off
	global_load_dwordx4 v[4:7], v[16:17], off offset:64
	global_load_dwordx4 v[8:11], v[16:17], off offset:128
	global_load_dwordx4 v[12:15], v[16:17], off offset:192
	v_cmp_gt_i32_e32 vcc, 8, v30
	s_and_saveexec_b64 s[0:1], vcc
	v_lshlrev_b32_e32 v16, 2, v30
	ds_write_b32 v16, v81 offset:35840
	s_or_b64 exec, exec, s[0:1]
	s_add_i32 s4, s3, 64
	v_ashrrev_i32_e32 v32, 4, v30
	s_add_u32 s0, s66, s4
	v_ashrrev_i32_e32 v33, 31, v32
	s_addc_u32 s1, s67, 0
	v_lshl_add_u64 v[16:17], s[0:1], 0, v[32:33]
	v_lshlrev_b64 v[16:17], 12, v[16:17]
	v_lshl_add_u64 v[16:17], s[60:61], 0, v[16:17]
	v_lshlrev_b32_e32 v18, 4, v30
	v_and_b32_e32 v83, 63, v30
	v_lshl_add_u64 v[16:17], v[16:17], 0, s[64:65]
	v_and_b32_e32 v34, 0xf0, v18
	v_mov_b32_e32 v35, v81
	s_waitcnt vmcnt(13)
	v_lshl_add_u64 v[24:25], v[16:17], 0, v[34:35]
	v_or_b32_e32 v16, s4, v83
	v_mov_b32_e32 v17, v81
	v_lshl_add_u64 v[16:17], s[66:67], 0, v[16:17]
	v_lshlrev_b64 v[16:17], 12, v[16:17]
	v_ashrrev_i32_e32 v31, 3, v30
	v_lshl_add_u64 v[16:17], s[62:63], 0, v[16:17]
	v_and_b32_e32 v86, -8, v31
	v_lshl_add_u64 v[26:27], v[16:17], 0, s[64:65]
	v_ashrrev_i32_e32 v87, 31, v86
	s_waitcnt vmcnt(12)
	v_lshl_add_u64 v[36:37], v[86:87], 1, v[26:27]
	global_load_dwordx4 v[16:19], v[24:25], off
	global_load_dwordx4 v[20:23], v[36:37], off
	v_add_u32_e32 v36, 0x200, v30
	v_ashrrev_i32_e32 v40, 4, v36
	v_ashrrev_i32_e32 v41, 31, v40
	v_lshl_add_u64 v[24:25], s[0:1], 0, v[40:41]
	v_lshlrev_b64 v[24:25], 12, v[24:25]
	v_lshl_add_u64 v[24:25], s[60:61], 0, v[24:25]
	v_ashrrev_i32_e32 v46, 3, v36
	v_lshl_add_u64 v[24:25], v[24:25], 0, s[64:65]
	v_and_b32_e32 v88, -8, v46
	v_lshl_add_u64 v[42:43], v[24:25], 0, v[34:35]
	v_ashrrev_i32_e32 v89, 31, v88
	v_lshl_add_u64 v[44:45], v[88:89], 1, v[26:27]
	global_load_dwordx4 v[24:27], v[42:43], off
	global_load_dwordx4 v[36:39], v[44:45], off
	s_add_u32 s0, s60, s64
	v_bfe_u32 v30, v30, 4, 2
	s_addc_u32 s1, s61, 0
	v_lshl_add_u64 v[92:93], s[66:67], 0, v[32:33]
	v_lshl_add_u64 v[94:95], s[66:67], 0, v[40:41]
	v_lshlrev_b32_e32 v110, 2, v29
	v_mul_lo_u32 v29, v32, s74
	v_or_b32_e32 v31, 7, v31
	v_mul_lo_u32 v32, v40, s74
	v_or_b32_e32 v40, 7, v46
	v_lshlrev_b32_e32 v42, 3, v30
	v_lshl_add_u64 v[90:91], s[0:1], 0, v[34:35]
	v_lshlrev_b32_e32 v35, 1, v83
	v_lshlrev_b32_e32 v109, 2, v30
	v_cmp_eq_u32_e64 s[6:7], 1, v30
	v_cmp_eq_u32_e64 s[8:9], 2, v30
	v_mul_lo_u32 v30, v86, s75
	v_mul_lo_u32 v31, v31, s75
	v_mul_lo_u32 v33, v88, s75
	v_mul_lo_u32 v40, v40, s75
	v_mul_u32_u24_e32 v41, 0x110, v28
	v_mul_u32_u24_e32 v28, 0x90, v28
	v_mov_b32_e32 v44, v81
	v_mov_b32_e32 v45, v81
	v_mov_b32_e32 v46, v81
	v_mov_b32_e32 v47, v81
	s_add_u32 s68, s62, s64
	v_add_u32_e32 v111, v34, v29
	v_add_u32_e32 v112, v35, v30
	v_add_u32_e32 v114, v35, v31
	v_add_u32_e32 v115, v34, v32
	v_add_u32_e32 v116, v35, v33
	v_add_u32_e32 v117, v35, v40
	v_add_u32_e32 v118, v80, v41
	v_add_u32_e32 v119, v42, v28
	v_mov_b64_e32 v[62:63], v[46:47]
	v_mov_b64_e32 v[58:59], v[46:47]
	v_mov_b64_e32 v[54:55], v[46:47]
	v_mov_b64_e32 v[50:51], v[46:47]
	v_mov_b64_e32 v[40:41], v[44:45]
	v_mov_b64_e32 v[32:33], v[44:45]
	v_mov_b64_e32 v[28:29], v[44:45]
	s_addc_u32 s69, s63, 0
	v_cmp_gt_u32_e64 s[4:5], 16, v83
	v_cmp_eq_u32_e64 s[10:11], 0, v83
	v_mov_b32_e32 v113, 0
	s_mov_b32 s64, s3
	v_mov_b64_e32 v[60:61], v[44:45]
	v_mov_b64_e32 v[56:57], v[44:45]
	v_mov_b64_e32 v[52:53], v[44:45]
	v_mov_b64_e32 v[48:49], v[44:45]
	v_mov_b64_e32 v[42:43], v[46:47]
	v_mov_b64_e32 v[34:35], v[46:47]
	v_mov_b64_e32 v[30:31], v[46:47]
	s_branch .LBB0_743

; __device__ void attn_item(const Params& p, int item, u16* O) {
;     ...
; #pragma unroll
;   for (int df = 0; df < 8; ++df) {
;     i32x2 ov = {(int)pack2(o[df][0], o[df][1]), (int)pack2(o[df][2], o[df][3])};
;     *(i32x2*)(O + (tb + qrow) * DM + hh * 128 + df * 16 + g4 * 4) = ov;
;   }
;   __syncthreads();
; template <int DUMMY>
; __device__ void phase2a(const Params& p) {
;     ...
;     if (threadIdx.x == 0) *slot = nxt;
.LBB0_783:
	v_lshlrev_b32_e32 v80, 1, v109
	s_waitcnt vmcnt(7)
	v_lshl_add_u64 v[0:1], v[84:85], 0, v[80:81]
	v_cvt_pk_bf16_f32 v2, v44, v45
	v_cvt_pk_bf16_f32 v3, v46, v47
	global_store_dwordx2 v[0:1], v[2:3], off
	v_cvt_pk_bf16_f32 v2, v60, v61
	v_cvt_pk_bf16_f32 v3, v62, v63
	global_store_dwordx2 v[0:1], v[2:3], off offset:32
	v_cvt_pk_bf16_f32 v2, v56, v57
	v_cvt_pk_bf16_f32 v3, v58, v59
	global_store_dwordx2 v[0:1], v[2:3], off offset:64
	v_cvt_pk_bf16_f32 v2, v52, v53
	v_cvt_pk_bf16_f32 v3, v54, v55
	global_store_dwordx2 v[0:1], v[2:3], off offset:96
	v_cvt_pk_bf16_f32 v2, v48, v49
	v_cvt_pk_bf16_f32 v3, v50, v51
	global_store_dwordx2 v[0:1], v[2:3], off offset:128
	v_cvt_pk_bf16_f32 v2, v40, v41
	v_cvt_pk_bf16_f32 v3, v42, v43
	global_store_dwordx2 v[0:1], v[2:3], off offset:160
	v_cvt_pk_bf16_f32 v2, v32, v33
	v_cvt_pk_bf16_f32 v3, v34, v35
	global_store_dwordx2 v[0:1], v[2:3], off offset:192
	v_cvt_pk_bf16_f32 v2, v28, v29
	v_cvt_pk_bf16_f32 v3, v30, v31
	global_store_dwordx2 v[0:1], v[2:3], off offset:224
	s_waitcnt lgkmcnt(0)
	s_barrier
	s_and_saveexec_b64 s[0:1], s[44:45]
	s_cbranch_execz .LBB0_734
	s_waitcnt vmcnt(8)
	ds_write_b32 v104, v250
	s_branch .LBB0_734
